# N2 fast path V-fragment reads as ds_read_b64 pairs
# baseline (speedup 1.0000x reference)
; __device__ __forceinline__ float exp2f_(float x) { return __builtin_amdgcn_exp2f(x); }
; __device__ __forceinline__ f32x4 mfma16(bf16x8 a, bf16x8 b, f32x4 c) { return __builtin_amdgcn_mfma_f32_16x16x32_bf16(a, b, c, 0, 0, 0); }
; __device__ __forceinline__ void nsa_block_step(const bf16_t* Ks, const bf16_t* VT, const bf16x8 (&qf)[2][2], f32x4 (&O)[2][4], float (&m)[2], float (&l)[2],
;                                                int klo, int khi, int r, int q) {
;     ...
;     bf16x8 pbv[2][2];
; #pragma unroll
;     for (int x = 0; x < 2; x++) {
;         float mx = fmaxf(fmaxf(fmaxf(s[x][0][0], s[x][0][1]), fmaxf(s[x][0][2], s[x][0][3])), fmaxf(fmaxf(s[x][1][0], s[x][1][1]), fmaxf(s[x][1][2], s[x][1][3])));
;         mx = fmaxf(mx, fmaxf(fmaxf(fmaxf(s[x][2][0], s[x][2][1]), fmaxf(s[x][2][2], s[x][2][3])), fmaxf(fmaxf(s[x][3][0], s[x][3][1]), fmaxf(s[x][3][2], s[x][3][3]))));
;         mx = xrow_max(mx);
;         const float mnew = fmaxf(m[x], mx);
;         const float alpha = exp2f_(m[x] - mnew);
;         m[x] = mnew;
;         float ls = 0.f;
; #pragma unroll
;         for (int kt = 0; kt < 4; kt++)
; #pragma unroll
;             for (int j = 0; j < 4; j++) { const float pv = exp2f_(s[x][kt][j] - mnew); s[x][kt][j] = pv; ls += pv; }
;         l[x] = l[x] * alpha + ls;
; #pragma unroll
;         for (int dt = 0; dt < 4; dt++) O[x][dt] *= alpha;
; #pragma unroll
;         for (int s2 = 0; s2 < 2; s2++) {
;             const u32x4 t4 = {pack2(s[x][2 * s2][0], s[x][2 * s2][1]), pack2(s[x][2 * s2][2], s[x][2 * s2][3]),
;                               pack2(s[x][2 * s2 + 1][0], s[x][2 * s2 + 1][1]), pack2(s[x][2 * s2 + 1][2], s[x][2 * s2 + 1][3])};
;             pbv[x][s2] = __builtin_bit_cast(bf16x8, t4);
;         }
;     }
; #pragma unroll
;     for (int s2 = 0; s2 < 2; s2++)
; #pragma unroll
;         for (int dt = 0; dt < 4; dt++) {
;             const u32x2 lo = *(const u32x2*)(VT + (dt * 16 + r) * 72 + (2 * s2) * 16 + 4 * q);
;             const u32x2 hi = *(const u32x2*)(VT + (dt * 16 + r) * 72 + (2 * s2 + 1) * 16 + 4 * q);
;             const bf16x8 va = mk_frag(lo, hi);
; #pragma unroll
;             for (int x = 0; x < 2; x++) O[x][dt] = mfma16(va, pbv[x][s2], O[x][dt]);
;         }
.Ln2_fast:
	ds_read_b64 v[200:201], v216
	ds_read_b64 v[202:203], v216 offset:32
	ds_read_b64 v[204:205], v217 offset:256
	ds_read_b64 v[206:207], v217 offset:288
	ds_read_b64 v[208:209], v218 offset:512
	ds_read_b64 v[210:211], v218 offset:544
	ds_read_b64 v[212:213], v219 offset:768
	ds_read_b64 v[214:215], v219 offset:800
	v_exp_f32_e32 v80, v80
	v_exp_f32_e32 v81, v81
	v_exp_f32_e32 v82, v82
	v_exp_f32_e32 v83, v83
	v_exp_f32_e32 v72, v72
	v_exp_f32_e32 v73, v73
	v_exp_f32_e32 v74, v74
	v_exp_f32_e32 v75, v75
	ds_read_b64 v[224:225], v216 offset:64
	ds_read_b64 v[226:227], v216 offset:96
	ds_read_b64 v[228:229], v217 offset:320
	ds_read_b64 v[230:231], v217 offset:352
	v_exp_f32_e32 v68, v68
	v_exp_f32_e32 v69, v69
	v_exp_f32_e32 v70, v70
	v_exp_f32_e32 v71, v71
	v_exp_f32_e32 v64, v64
	v_exp_f32_e32 v65, v65
	v_exp_f32_e32 v66, v66
	v_exp_f32_e32 v67, v67
	ds_read_b64 v[232:233], v218 offset:576
	ds_read_b64 v[234:235], v218 offset:608
	v_cvt_pk_bf16_f32 v184, v80, v81
	v_cvt_pk_bf16_f32 v185, v82, v83
	v_cvt_pk_bf16_f32 v186, v72, v73
	v_cvt_pk_bf16_f32 v187, v74, v75
	v_cvt_pk_bf16_f32 v192, v68, v69
	v_cvt_pk_bf16_f32 v193, v70, v71
	v_cvt_pk_bf16_f32 v194, v64, v65
	v_cvt_pk_bf16_f32 v195, v66, v67
	v_exp_f32_e32 v84, v84
	v_exp_f32_e32 v85, v85
	s_waitcnt lgkmcnt(12)
	v_mfma_f32_16x16x32_bf16 v[52:55], v[200:203], v[184:187], v[52:55]
	v_exp_f32_e32 v86, v86
	v_exp_f32_e32 v87, v87
	v_mfma_f32_16x16x32_bf16 v[36:39], v[200:203], v[192:195], v[36:39]
	ds_read_b64 v[236:237], v219 offset:832
	ds_read_b64 v[238:239], v219 offset:864
	v_exp_f32_e32 v76, v76
	v_exp_f32_e32 v77, v77
	s_waitcnt lgkmcnt(12)
	v_mfma_f32_16x16x32_bf16 v[48:51], v[204:207], v[184:187], v[48:51]
	v_exp_f32_e32 v78, v78
	v_exp_f32_e32 v79, v79
	v_mfma_f32_16x16x32_bf16 v[32:35], v[204:207], v[192:195], v[32:35]
	v_exp_f32_e32 v60, v60
	v_exp_f32_e32 v61, v61
	s_waitcnt lgkmcnt(10)
	v_mfma_f32_16x16x32_bf16 v[44:47], v[208:211], v[184:187], v[44:47]
	v_exp_f32_e32 v62, v62
	v_exp_f32_e32 v63, v63
	v_mfma_f32_16x16x32_bf16 v[28:31], v[208:211], v[192:195], v[28:31]
	v_exp_f32_e32 v56, v56
	v_exp_f32_e32 v57, v57
	s_waitcnt lgkmcnt(8)
	v_mfma_f32_16x16x32_bf16 v[40:43], v[212:215], v[184:187], v[40:43]
	v_exp_f32_e32 v58, v58
	v_exp_f32_e32 v59, v59
	v_mfma_f32_16x16x32_bf16 v[24:27], v[212:215], v[192:195], v[24:27]
	v_cvt_pk_bf16_f32 v188, v84, v85
	v_cvt_pk_bf16_f32 v189, v86, v87
	v_cvt_pk_bf16_f32 v190, v76, v77
	v_cvt_pk_bf16_f32 v191, v78, v79
	v_cvt_pk_bf16_f32 v196, v60, v61
	v_cvt_pk_bf16_f32 v197, v62, v63
	v_cvt_pk_bf16_f32 v198, v56, v57
	v_cvt_pk_bf16_f32 v199, v58, v59
	v_add_f32_e32 v221, v80, v81
	v_add_f32_e32 v220, v68, v69
	s_waitcnt lgkmcnt(6)
	v_mfma_f32_16x16x32_bf16 v[52:55], v[224:227], v[188:191], v[52:55]
	v_add_f32_e32 v221, v221, v82
	v_add_f32_e32 v220, v220, v70
	v_mfma_f32_16x16x32_bf16 v[36:39], v[224:227], v[196:199], v[36:39]
	v_add_f32_e32 v221, v221, v83
	v_add_f32_e32 v220, v220, v71
	s_waitcnt lgkmcnt(4)
	v_mfma_f32_16x16x32_bf16 v[48:51], v[228:231], v[188:191], v[48:51]
	v_add_f32_e32 v221, v221, v72
	v_add_f32_e32 v220, v220, v64
	v_mfma_f32_16x16x32_bf16 v[32:35], v[228:231], v[196:199], v[32:35]
	v_add_f32_e32 v221, v221, v73
	v_add_f32_e32 v220, v220, v65
	s_waitcnt lgkmcnt(2)
	v_mfma_f32_16x16x32_bf16 v[44:47], v[232:235], v[188:191], v[44:47]
	v_add_f32_e32 v221, v221, v74
	v_add_f32_e32 v220, v220, v66
	v_mfma_f32_16x16x32_bf16 v[28:31], v[232:235], v[196:199], v[28:31]
	v_add_f32_e32 v221, v221, v75
	v_add_f32_e32 v220, v220, v67
	s_waitcnt lgkmcnt(0)
	v_mfma_f32_16x16x32_bf16 v[40:43], v[236:239], v[188:191], v[40:43]
	v_add_f32_e32 v221, v221, v84
	v_add_f32_e32 v220, v220, v60
	v_mfma_f32_16x16x32_bf16 v[24:27], v[236:239], v[196:199], v[24:27]
	v_add_f32_e32 v221, v221, v85
	v_add_f32_e32 v220, v220, v61
	v_add_f32_e32 v221, v221, v86
	v_add_f32_e32 v220, v220, v62
	v_add_f32_e32 v221, v221, v87
	v_add_f32_e32 v220, v220, v63
	v_add_f32_e32 v221, v221, v76
	v_add_f32_e32 v220, v220, v56
	v_add_f32_e32 v221, v221, v77
	v_add_f32_e32 v220, v220, v57
	v_add_f32_e32 v221, v221, v78
	v_add_f32_e32 v220, v220, v58
	v_add_f32_e32 v221, v221, v79
	v_add_f32_e32 v220, v220, v59
	v_cmp_ne_u32_e32 vcc, v141, v143
	v_mov_b32_e32 v88, v103
	v_mov_b32_e32 v97, v102
	v_pk_add_f32 v[100:101], v[100:101], v[220:221]
	s_branch .Ln2_tail
